# v33 + W_up layer-0 conversion moved to the idle workgroups of NSA-in round 3, ML weights to the layer-0 up-proj window; phase 0 converts only NSA weights
# speedup vs baseline: 1.0137x; 1.0037x over previous
.LBB0_9:
	s_lshr_b32 s87, s2, 6
	s_load_dwordx2 s[2:3], s[0:1], 0x48
	v_and_b32_e32 v21, 31, v0
	v_bfe_u32 v31, v0, 5, 1
	v_lshlrev_b32_e32 v2, 2, v21
	v_mul_u32_u24_e32 v3, 0x84, v31
	s_waitcnt lgkmcnt(0)
	v_writelane_b32 v254, s2, 8
	v_bfe_u32 v29, v0, 3, 3
	s_lshl_b32 s43, s38, 3
	v_writelane_b32 v254, s3, 9
	s_lshl_b32 s2, s87, 14
	s_add_i32 s3, s2, 0
	v_readlane_b32 s4, v254, 2
	v_add3_u32 v28, s3, v2, v3
	v_lshlrev_b32_e32 v2, 3, v0
	s_lshl_b32 s2, s4, 3
	v_and_b32_e32 v2, 56, v2
	v_readlane_b32 s5, v254, 3
	v_writelane_b32 v254, s2, 10
	s_add_i32 s2, s2, s87
	v_mul_u32_u24_e32 v4, 0x84, v2
	v_lshlrev_b32_e32 v5, 2, v29
	s_movk_i32 s100, 0x77f
	s_mov_b32 s101, 0
	s_mov_b32 s7, 0
	s_cmp_gt_i32 s2, s100
	v_mov_b32_e32 v3, 0
	v_add3_u32 v30, s3, v4, v5
	v_lshlrev_b32_e32 v18, 1, v2
	s_cbranch_scc1 .LBB0_160

.LBB0_160:
	s_cmp_eq_u32 s101, 1
	s_cbranch_scc1 .Lcv1_ret
	s_cmp_lg_u32 s101, 0
	s_cbranch_scc1 .Lcv_relay_ret
	s_mov_b64 s[76:77], s[88:89]
	v_and_b32_e32 v20, 63, v0
	s_cmpk_gt_i32 s2, 0x407f
	v_mbcnt_lo_u32_b32 v166, -1, 0
	s_mov_b32 s72, s86
	s_mov_b64 s[78:79], s[90:91]
	s_cbranch_scc1 .LBB0_165
	v_mbcnt_hi_u32_b32 v4, -1, v166
	v_and_b32_e32 v5, 64, v4
	v_add_u32_e32 v5, 64, v5
	v_xor_b32_e32 v6, 1, v4
	v_cmp_lt_i32_e32 vcc, v6, v5
	s_load_dwordx2 s[4:5], s[0:1], 0x48
	v_mov_b32_e32 v3, 0
	v_cndmask_b32_e32 v6, v4, v6, vcc
	v_lshlrev_b32_e32 v19, 2, v6
	v_xor_b32_e32 v6, 2, v4
	v_cmp_lt_i32_e32 vcc, v6, v5
	v_lshlrev_b32_e32 v2, 4, v20
	s_waitcnt lgkmcnt(0)
	v_lshl_add_u64 v[22:23], s[4:5], 0, v[2:3]
	v_cndmask_b32_e32 v6, v4, v6, vcc
	v_lshlrev_b32_e32 v32, 2, v6
	v_xor_b32_e32 v6, 4, v4
	v_cmp_lt_i32_e32 vcc, v6, v5
	s_mov_b64 s[4:5], 0x4200000
	v_lshl_add_u64 v[26:27], s[76:77], 0, v[2:3]
	v_cndmask_b32_e32 v6, v4, v6, vcc
	v_lshlrev_b32_e32 v33, 2, v6
	v_xor_b32_e32 v6, 8, v4
	v_cmp_lt_i32_e32 vcc, v6, v5
	v_lshlrev_b32_e32 v37, 4, v20
	v_mov_b32_e32 v38, 0x358637bd
	v_cndmask_b32_e32 v6, v4, v6, vcc
	v_lshlrev_b32_e32 v34, 2, v6
	v_xor_b32_e32 v6, 16, v4
	v_cmp_lt_i32_e32 vcc, v6, v5
	s_mov_b32 s3, 0xf800000
	v_mov_b32_e32 v39, 0x260
	v_cndmask_b32_e32 v6, v4, v6, vcc
	v_lshlrev_b32_e32 v35, 2, v6
	v_xor_b32_e32 v6, 32, v4
	v_cmp_lt_i32_e32 vcc, v6, v5
	v_mov_b32_e32 v5, v3
	s_nop 0
	v_cndmask_b32_e32 v4, v4, v6, vcc
	v_lshlrev_b32_e32 v36, 2, v4
	v_lshlrev_b32_e32 v4, 3, v20
	v_lshl_add_u64 v[4:5], s[78:79], 0, v[4:5]
	v_lshl_add_u64 v[24:25], v[4:5], 0, s[4:5]
	s_mov_b32 s4, s2
	s_branch .LBB0_163

.LBB0_640:
	s_waitcnt vmcnt(0)
	s_barrier
	s_cmpk_lt_u32 s86, 203
	s_cbranch_scc1 .Lcv1_skip
	v_writelane_b32 v200, s2, 0
	v_writelane_b32 v200, s3, 1
	v_writelane_b32 v200, s4, 2
	v_writelane_b32 v200, s5, 3
	v_writelane_b32 v200, s6, 4
	v_writelane_b32 v200, s7, 5
	v_writelane_b32 v200, s8, 6
	v_writelane_b32 v200, s9, 7
	v_writelane_b32 v200, s10, 8
	v_writelane_b32 v200, s11, 9
	v_writelane_b32 v200, s12, 10
	v_writelane_b32 v200, s13, 11
	v_writelane_b32 v200, s14, 12
	v_writelane_b32 v200, s15, 13
	v_writelane_b32 v200, s16, 14
	v_writelane_b32 v200, s17, 15
	v_writelane_b32 v200, s18, 16
	v_writelane_b32 v200, s19, 17
	v_writelane_b32 v200, s20, 18
	v_writelane_b32 v200, s21, 19
	v_writelane_b32 v200, s22, 20
	v_writelane_b32 v200, s23, 21
	v_writelane_b32 v200, s24, 22
	v_writelane_b32 v200, s25, 23
	v_writelane_b32 v200, s26, 24
	v_writelane_b32 v200, s27, 25
	v_writelane_b32 v200, s28, 26
	v_writelane_b32 v200, s29, 27
	v_writelane_b32 v200, s30, 28
	v_writelane_b32 v200, s31, 29
	v_writelane_b32 v200, s32, 30
	v_writelane_b32 v200, s33, 31
	v_writelane_b32 v200, s34, 32
	v_writelane_b32 v200, s35, 33
	v_writelane_b32 v200, s36, 34
	v_writelane_b32 v200, s37, 35
	v_writelane_b32 v200, s38, 36
	v_writelane_b32 v200, s39, 37
	v_writelane_b32 v200, s40, 38
	v_writelane_b32 v200, s41, 39
	v_writelane_b32 v200, s42, 40
	v_writelane_b32 v200, s43, 41
	v_writelane_b32 v200, s44, 42
	v_writelane_b32 v200, s45, 43
	v_writelane_b32 v200, s46, 44
	v_writelane_b32 v200, s47, 45
	v_writelane_b32 v200, s48, 46
	v_writelane_b32 v200, s49, 47
	v_writelane_b32 v200, s50, 48
	v_writelane_b32 v200, s51, 49
	v_writelane_b32 v200, s52, 50
	v_writelane_b32 v200, s53, 51
	v_writelane_b32 v200, s54, 52
	v_writelane_b32 v200, s55, 53
	v_writelane_b32 v200, s56, 54
	v_writelane_b32 v200, s57, 55
	v_writelane_b32 v200, s58, 56
	v_writelane_b32 v200, s59, 57
	v_writelane_b32 v200, s60, 58
	v_writelane_b32 v200, s61, 59
	v_writelane_b32 v200, s62, 60
	v_writelane_b32 v200, s63, 61
	v_writelane_b32 v200, s64, 62
	v_writelane_b32 v200, s65, 63
	v_writelane_b32 v201, s66, 0
	v_writelane_b32 v201, s67, 1
	v_writelane_b32 v201, s68, 2
	v_writelane_b32 v201, s69, 3
	v_writelane_b32 v201, s70, 4
	v_writelane_b32 v201, s71, 5
	v_writelane_b32 v201, s72, 6
	v_writelane_b32 v201, s73, 7
	v_writelane_b32 v201, s74, 8
	v_writelane_b32 v201, s75, 9
	v_writelane_b32 v201, s76, 10
	v_writelane_b32 v201, s77, 11
	v_writelane_b32 v201, s78, 12
	v_writelane_b32 v201, s79, 13
	v_writelane_b32 v201, s80, 14
	v_writelane_b32 v201, s81, 15
	v_writelane_b32 v201, s82, 16
	v_writelane_b32 v201, s83, 17
	v_writelane_b32 v201, s84, 18
	v_writelane_b32 v201, s85, 19
	v_writelane_b32 v201, s86, 20
	v_writelane_b32 v201, s87, 21
	v_writelane_b32 v201, s88, 22
	v_writelane_b32 v201, s89, 23
	v_writelane_b32 v201, s90, 24
	v_writelane_b32 v201, s91, 25
	v_writelane_b32 v201, s92, 26
	v_writelane_b32 v201, s93, 27
	v_writelane_b32 v201, s94, 28
	v_writelane_b32 v201, s95, 29
	v_writelane_b32 v201, s96, 30
	v_writelane_b32 v201, s97, 31
	v_writelane_b32 v201, s98, 32
	v_writelane_b32 v201, s99, 33
	v_mbcnt_lo_u32_b32 v0, -1, 0
	v_mbcnt_hi_u32_b32 v0, -1, v0
	v_and_b32_e32 v21, 31, v0
	v_bfe_u32 v31, v0, 5, 1
	v_lshlrev_b32_e32 v2, 2, v21
	v_mul_u32_u24_e32 v3, 0x84, v31
	v_bfe_u32 v29, v0, 3, 3
	s_lshl_b32 s2, s87, 14
	s_add_i32 s3, s2, 0
	v_add3_u32 v28, s3, v2, v3
	v_lshlrev_b32_e32 v2, 3, v0
	v_and_b32_e32 v2, 56, v2
	v_mul_u32_u24_e32 v4, 0x84, v2
	v_lshlrev_b32_e32 v5, 2, v29
	s_mov_b32 s7, 0
	v_mov_b32_e32 v3, 0
	v_add3_u32 v30, s3, v4, v5
	v_lshlrev_b32_e32 v18, 1, v2
	s_sub_i32 s2, s86, 203
	s_lshl_b32 s2, s2, 3
	s_add_i32 s2, s2, s87
	s_addk_i32 s2, 0x1000
	s_movk_i32 s43, 0x1a8
	s_movk_i32 s100, 0x1fff
	s_mov_b32 s101, 1
	s_branch .Lcv_loop_entry

.Lcv1_skip:
	s_waitcnt vmcnt(0)
	v_readlane_b32 s2, v254, 6
	v_readlane_b32 s3, v254, 7
	s_and_b64 vcc, exec, s[2:3]
	s_barrier
	s_cbranch_vccz .LBB0_686
	s_mov_b32 s2, -1
	s_nop 0
	v_mbcnt_lo_u32_b32 v0, s2, 0
	v_mbcnt_hi_u32_b32 v0, s2, v0
	v_cmp_eq_u32_e32 vcc, 0, v0
	s_and_saveexec_b64 s[36:37], vcc
	s_cbranch_execz .LBB0_685
	v_readlane_b32 s44, v254, 4
	s_add_i32 s3, 0, 0x24160
	v_readlane_b32 s45, v254, 5
	s_mov_b32 s2, s85
	v_mov_b32_e32 v0, s3
	s_waitcnt vmcnt(0) expcnt(0) lgkmcnt(0)
	ds_read_b32 v2, v0
	s_add_i32 s3, 0, 0x24164
	v_mov_b32_e32 v0, s3
	ds_read_b32 v0, v0
	s_waitcnt lgkmcnt(1)
	v_cmp_ne_u32_e32 vcc, 0, v2
	s_cbranch_vccnz .LBB0_656
	v_readlane_b32 s6, v254, 0
	v_readlane_b32 s7, v254, 1
	s_load_dwordx2 s[4:5], s[6:7], 0x4
	s_add_u32 s6, s44, 0x1000
	s_addc_u32 s7, s45, 0
	s_add_u32 s8, s44, 0x1100
	s_addc_u32 s9, s45, 0
	s_add_u32 s10, s44, 0x1200
	s_addc_u32 s11, s45, 0
	s_add_u32 s12, s44, 0x1300
	s_waitcnt lgkmcnt(0)
	s_mul_i32 s3, s4, s38
	s_addc_u32 s13, s45, 0
	s_mul_i32 s3, s3, s5
	s_mov_b32 s22, 1
	s_mov_b64 s[4:5], 0
	v_mov_b64_e32 v[0:1], s[44:45]
	v_mov_b64_e32 v[2:3], s[6:7]
	v_mov_b64_e32 v[4:5], s[8:9]
	v_mov_b64_e32 v[6:7], s[10:11]
	v_mov_b64_e32 v[8:9], s[12:13]
	s_branch .LBB0_646

.Lcv2_ret:
	s_cmp_eq_u32 s101, 3
	s_cbranch_scc1 .Lcv2_done
	v_readlane_b32 s2, v254, 19
	v_readlane_b32 s87, v255, 4
	s_sub_i32 s2, s2, 32
	s_lshl_b32 s2, s2, 3
	s_add_i32 s2, s2, s87
	s_addk_i32 s2, 0x780
	s_movk_i32 s43, 0x700
	s_movk_i32 s100, 0xfff
	s_mov_b32 s101, 3
	s_mov_b32 s7, 0
	s_branch .Lcv_relay_fwd
